# P0 tail: context K/V cache conversion loads (3+1 trips) all issued up front instead of one load round trip per trip
# baseline (speedup 1.0000x reference)
.LBB0_122:
	s_cmp_lg_u32 s58, 0x20000
	s_cbranch_scc1 .Lp0t_loop
	v_ashrrev_i32_e32 v10, 14, v9
	v_lshrrev_b32_e32 v6, 6, v9
	v_lshrrev_b32_e32 v13, 1, v9
	v_mul_hi_i32 v15, v10, s1
	v_mul_hi_i32 v11, v9, s1
	v_and_b32_e32 v14, 0xf8, v6
	v_and_b32_e32 v6, 0xfc, v13
	v_lshrrev_b32_e32 v13, 31, v15
	v_lshrrev_b32_e32 v16, 31, v11
	v_lshrrev_b32_e32 v11, 14, v11
	v_add_u32_e32 v13, v15, v13
	v_add_lshl_u32 v11, v11, v16, 8
	v_mul_lo_u32 v13, v13, 6
	v_or3_b32 v11, v8, v14, v11
	v_sub_u32_e32 v10, v10, v13
	v_mad_i32_i24 v10, v11, 6, v10
	v_ashrrev_i32_e32 v11, 31, v10
	v_lshlrev_b64 v[10:11], 8, v[10:11]
	global_load_dword v100, v[4:5], off
	v_lshl_add_u64 v[10:11], s[10:11], 0, v[10:11]
	v_lshl_add_u64 v[102:103], v[10:11], 0, v[6:7]
	global_load_dword v101, v[102:103], off
	v_add_co_u32_e32 v104, vcc, 0xfff40000, v2
	v_add_u32_e32 v9, s58, v9
	s_nop 0
	v_addc_co_u32_e32 v105, vcc, -1, v3, vcc
	v_mov_b32_e32 v106, v2
	v_mov_b32_e32 v107, v3
	v_lshl_add_u64 v[4:5], v[4:5], 0, s[8:9]
	v_lshl_add_u64 v[2:3], v[2:3], 0, s[6:7]
	v_ashrrev_i32_e32 v10, 14, v9
	v_lshrrev_b32_e32 v6, 6, v9
	v_lshrrev_b32_e32 v13, 1, v9
	v_mul_hi_i32 v15, v10, s1
	v_mul_hi_i32 v11, v9, s1
	v_and_b32_e32 v14, 0xf8, v6
	v_and_b32_e32 v6, 0xfc, v13
	v_lshrrev_b32_e32 v13, 31, v15
	v_lshrrev_b32_e32 v16, 31, v11
	v_lshrrev_b32_e32 v11, 14, v11
	v_add_u32_e32 v13, v15, v13
	v_add_lshl_u32 v11, v11, v16, 8
	v_mul_lo_u32 v13, v13, 6
	v_or3_b32 v11, v8, v14, v11
	v_sub_u32_e32 v10, v10, v13
	v_mad_i32_i24 v10, v11, 6, v10
	v_ashrrev_i32_e32 v11, 31, v10
	v_lshlrev_b64 v[10:11], 8, v[10:11]
	global_load_dword v108, v[4:5], off
	v_lshl_add_u64 v[10:11], s[10:11], 0, v[10:11]
	v_lshl_add_u64 v[110:111], v[10:11], 0, v[6:7]
	global_load_dword v109, v[110:111], off
	v_add_co_u32_e32 v112, vcc, 0xfff40000, v2
	v_add_u32_e32 v9, s58, v9
	s_nop 0
	v_addc_co_u32_e32 v113, vcc, -1, v3, vcc
	v_mov_b32_e32 v114, v2
	v_mov_b32_e32 v115, v3
	v_lshl_add_u64 v[4:5], v[4:5], 0, s[8:9]
	v_lshl_add_u64 v[2:3], v[2:3], 0, s[6:7]
	v_ashrrev_i32_e32 v10, 14, v9
	v_lshrrev_b32_e32 v6, 6, v9
	v_lshrrev_b32_e32 v13, 1, v9
	v_mul_hi_i32 v15, v10, s1
	v_mul_hi_i32 v11, v9, s1
	v_and_b32_e32 v14, 0xf8, v6
	v_and_b32_e32 v6, 0xfc, v13
	v_lshrrev_b32_e32 v13, 31, v15
	v_lshrrev_b32_e32 v16, 31, v11
	v_lshrrev_b32_e32 v11, 14, v11
	v_add_u32_e32 v13, v15, v13
	v_add_lshl_u32 v11, v11, v16, 8
	v_mul_lo_u32 v13, v13, 6
	v_or3_b32 v11, v8, v14, v11
	v_sub_u32_e32 v10, v10, v13
	v_mad_i32_i24 v10, v11, 6, v10
	v_ashrrev_i32_e32 v11, 31, v10
	v_lshlrev_b64 v[10:11], 8, v[10:11]
	global_load_dword v116, v[4:5], off
	v_lshl_add_u64 v[10:11], s[10:11], 0, v[10:11]
	v_lshl_add_u64 v[118:119], v[10:11], 0, v[6:7]
	global_load_dword v117, v[118:119], off
	v_add_co_u32_e32 v120, vcc, 0xfff40000, v2
	v_add_u32_e32 v9, s58, v9
	s_nop 0
	v_addc_co_u32_e32 v121, vcc, -1, v3, vcc
	v_mov_b32_e32 v122, v2
	v_mov_b32_e32 v123, v3
	v_lshl_add_u64 v[4:5], v[4:5], 0, s[8:9]
	v_lshl_add_u64 v[2:3], v[2:3], 0, s[6:7]
	v_lshl_add_u64 v[130:131], v[0:1], 2, s[12:13]
	v_lshrrev_b32_e32 v132, 6, v0
	v_ashrrev_i32_e32 v133, 7, v0
	v_and_b32_e32 v134, 0xf8, v132
	v_and_b32_e32 v133, 0xffffff00, v133
	v_or3_b32 v134, v134, v8, v133
	v_ashrrev_i32_e32 v135, 31, v134
	v_lshlrev_b64 v[134:135], 9, v[134:135]
	v_lshrrev_b32_e32 v133, 1, v0
	v_and_b32_e32 v136, 0x100, v132
	v_mov_b32_e32 v137, 0
	v_lshl_add_u64 v[134:135], s[14:15], 0, v[134:135]
	global_load_dword v124, v[130:131], off
	v_lshl_add_u64 v[134:135], v[134:135], 0, v[136:137]
	v_and_b32_e32 v136, 0xfc, v133
	v_lshl_add_u64 v[134:135], v[134:135], 0, v[136:137]
	global_load_dword v125, v[134:135], off
	s_waitcnt vmcnt(2)
	v_bfe_u32 v13, v100, 16, 1
	v_add3_u32 v100, v100, v13, s0
	global_store_short_d16_hi v[104:105], v100, off
	v_bfe_u32 v13, v101, 16, 1
	v_add3_u32 v101, v101, v13, s0
	global_store_short_d16_hi v[106:107], v101, off
	v_bfe_u32 v13, v108, 16, 1
	v_add3_u32 v108, v108, v13, s0
	global_store_short_d16_hi v[112:113], v108, off
	v_bfe_u32 v13, v109, 16, 1
	v_add3_u32 v109, v109, v13, s0
	global_store_short_d16_hi v[114:115], v109, off
	v_bfe_u32 v13, v116, 16, 1
	v_add3_u32 v116, v116, v13, s0
	global_store_short_d16_hi v[120:121], v116, off
	v_bfe_u32 v13, v117, 16, 1
	v_add3_u32 v117, v117, v13, s0
	global_store_short_d16_hi v[122:123], v117, off
	s_branch .LBB0_123

.LBB0_136:
	s_cmp_lg_u32 s58, 0x20000
	s_cbranch_scc1 .Lp0t_loop2
	v_add_co_u32_e32 v10, vcc, 0xfffc0000, v2
	s_nop 1
	v_addc_co_u32_e32 v11, vcc, -1, v3, vcc
	s_waitcnt vmcnt(0)
	v_bfe_u32 v9, v124, 16, 1
	v_add3_u32 v1, v124, v9, s0
	global_store_short_d16_hi v[10:11], v1, off
	v_bfe_u32 v9, v125, 16, 1
	v_add3_u32 v1, v125, v9, s0
	global_store_short_d16_hi v[2:3], v1, off
	s_branch .LBB0_137
